# lean grid barrier at the four remaining sites: per-XCD arrival + one global counter polled by every workgroup (no top-level returning add / relay)
# speedup vs baseline: 1.0038x; 1.0017x over previous
.LBB0_491:
	s_waitcnt vmcnt(0)
	v_readlane_b32 s0, v252, 35
	v_readlane_b32 s1, v252, 36
	s_and_b64 vcc, exec, s[0:1]
	s_waitcnt lgkmcnt(0)
	s_barrier
	s_cbranch_vccnz .LBB0_552
	s_mov_b64 exec, 1
	s_getreg_b32 s100, hwreg(HW_REG_XCC_ID, 0, 4)
	v_readlane_b32 s98, v252, 25
	v_readlane_b32 s99, v252, 26
	s_lshl_b32 s100, s100, 8
	s_add_u32 s100, s100, 5248
	v_mov_b32_e32 v255, s100
	v_mov_b32_e32 v254, 1
	s_nop 2
	global_atomic_add v254, v255, v254, s[98:99] sc0
	s_waitcnt vmcnt(0)
	v_readfirstlane_b32 s100, v254
	v_mov_b32_e32 v255, 13440
	s_cmp_eq_u32 s100, 31
	s_cbranch_scc0 .Lgb2_poll
	buffer_wbl2 sc1
	s_waitcnt vmcnt(0)
	v_mov_b32_e32 v254, 1
	global_atomic_add v255, v254, s[98:99]
.Lgb2_poll:
	s_mov_b32 s101, 0
.Lgb2_loop:
	global_load_dword v254, v255, s[98:99] sc1
	s_waitcnt vmcnt(0)
	v_readfirstlane_b32 s100, v254
	s_cmp_ge_u32 s100, 8
	s_cbranch_scc1 .Lgb2_done
	s_sleep 1
	s_add_i32 s101, s101, 1
	s_cmp_lt_u32 s101, 0x40000
	s_cbranch_scc1 .Lgb2_loop
.Lgb2_done:
	buffer_inv sc1
	s_waitcnt vmcnt(0)
	s_mov_b64 exec, -1

.LBB0_696:
	s_waitcnt vmcnt(0)
	v_readlane_b32 s0, v252, 35
	v_readlane_b32 s1, v252, 36
	s_and_b64 vcc, exec, s[0:1]
	s_waitcnt vmcnt(63) expcnt(7) lgkmcnt(15)
	s_barrier
	s_cbranch_vccnz .LBB0_757
	s_mov_b64 exec, 1
	s_getreg_b32 s100, hwreg(HW_REG_XCC_ID, 0, 4)
	v_readlane_b32 s98, v252, 25
	v_readlane_b32 s99, v252, 26
	s_lshl_b32 s100, s100, 8
	s_add_u32 s100, s100, 5248
	v_mov_b32_e32 v255, s100
	v_mov_b32_e32 v254, 1
	s_nop 2
	global_atomic_add v254, v255, v254, s[98:99] sc0
	s_waitcnt vmcnt(0)
	v_readfirstlane_b32 s100, v254
	v_mov_b32_e32 v255, 13440
	s_cmp_eq_u32 s100, 63
	s_cbranch_scc0 .Lgb3_poll
	buffer_wbl2 sc1
	s_waitcnt vmcnt(0)
	v_mov_b32_e32 v254, 1
	global_atomic_add v255, v254, s[98:99]

.Lgb3_loop:
	global_load_dword v254, v255, s[98:99] sc1
	s_waitcnt vmcnt(0)
	v_readfirstlane_b32 s100, v254
	s_cmp_ge_u32 s100, 16
	s_cbranch_scc1 .Lgb3_done
	s_sleep 1
	s_add_i32 s101, s101, 1
	s_cmp_lt_u32 s101, 0x40000
	s_cbranch_scc1 .Lgb3_loop

.LBB0_808:
	s_waitcnt vmcnt(0)
	v_readlane_b32 s0, v252, 35
	v_readlane_b32 s1, v252, 36
	s_and_b64 vcc, exec, s[0:1]
	s_barrier
	s_cbranch_vccnz .LBB0_869
	s_mov_b64 exec, 1
	s_getreg_b32 s100, hwreg(HW_REG_XCC_ID, 0, 4)
	v_readlane_b32 s98, v252, 25
	v_readlane_b32 s99, v252, 26
	s_lshl_b32 s100, s100, 8
	s_add_u32 s100, s100, 5248
	v_mov_b32_e32 v255, s100
	v_mov_b32_e32 v254, 1
	s_nop 2
	global_atomic_add v254, v255, v254, s[98:99] sc0
	s_waitcnt vmcnt(0)
	v_readfirstlane_b32 s100, v254
	v_mov_b32_e32 v255, 13440
	s_cmp_eq_u32 s100, 95
	s_cbranch_scc0 .Lgb4_poll
	buffer_wbl2 sc1
	s_waitcnt vmcnt(0)
	v_mov_b32_e32 v254, 1
	global_atomic_add v255, v254, s[98:99]

.Lgb4_loop:
	global_load_dword v254, v255, s[98:99] sc1
	s_waitcnt vmcnt(0)
	v_readfirstlane_b32 s100, v254
	s_cmp_ge_u32 s100, 24
	s_cbranch_scc1 .Lgb4_done
	s_sleep 1
	s_add_i32 s101, s101, 1
	s_cmp_lt_u32 s101, 0x40000
	s_cbranch_scc1 .Lgb4_loop

.LBB0_915:
	s_waitcnt vmcnt(0)
	v_readlane_b32 s0, v252, 35
	v_readlane_b32 s1, v252, 36
	v_readlane_b32 s56, v252, 1
	v_readlane_b32 s54, v252, 33
	s_and_b64 vcc, exec, s[0:1]
	v_readlane_b32 s57, v252, 2
	v_readlane_b32 s58, v252, 3
	v_readlane_b32 s59, v252, 4
	v_readlane_b32 s55, v252, 34
	s_barrier
	v_readlane_b32 s60, v252, 5
	v_readlane_b32 s61, v252, 6
	v_readlane_b32 s62, v252, 7
	v_readlane_b32 s63, v252, 8
	v_readlane_b32 s64, v252, 9
	v_readlane_b32 s65, v252, 10
	v_readlane_b32 s66, v252, 11
	v_readlane_b32 s67, v252, 12
	v_readlane_b32 s68, v252, 13
	v_readlane_b32 s69, v252, 14
	v_readlane_b32 s70, v252, 15
	v_readlane_b32 s71, v252, 16
	s_cbranch_vccnz .LBB0_976
	s_mov_b64 exec, 1
	s_getreg_b32 s100, hwreg(HW_REG_XCC_ID, 0, 4)
	v_readlane_b32 s98, v252, 25
	v_readlane_b32 s99, v252, 26
	s_lshl_b32 s100, s100, 8
	s_add_u32 s100, s100, 5248
	v_mov_b32_e32 v255, s100
	v_mov_b32_e32 v254, 1
	s_nop 2
	global_atomic_add v254, v255, v254, s[98:99] sc0
	s_waitcnt vmcnt(0)
	v_readfirstlane_b32 s100, v254
	v_mov_b32_e32 v255, 13440
	s_cmp_eq_u32 s100, 127
	s_cbranch_scc0 .Lgb5_poll
	buffer_wbl2 sc1
	s_waitcnt vmcnt(0)
	v_mov_b32_e32 v254, 1
	global_atomic_add v255, v254, s[98:99]

.Lgb5_loop:
	global_load_dword v254, v255, s[98:99] sc1
	s_waitcnt vmcnt(0)
	v_readfirstlane_b32 s100, v254
	s_cmp_ge_u32 s100, 32
	s_cbranch_scc1 .Lgb5_done
	s_sleep 1
	s_add_i32 s101, s101, 1
	s_cmp_lt_u32 s101, 0x40000
	s_cbranch_scc1 .Lgb5_loop
